# P2 diff loop: row-sum adds of a tile deferred into the PV MFMAs of the next step and cvt P0 rides the S1 MFMAs, shortening the VALU-only tail of each step
# speedup vs baseline: 1.0068x; 1.0013x over previous
; #define ATT_KREAD(dst, c) do { _Pragma("unroll") for (int kb = 0; kb < 4; ++kb) _Pragma("unroll") for (int ds = 0; ds < 2; ++ds) \
;                 dst[kb * 2 + ds] = *(const LAS bf16x8*)(bp + (c) * 8192 + kb * 2048 + kfo + (((unsigned)(4 * ds + quad) ^ ksw) * 16)); } while (0)
; #define ATT_SMMA(sv, kf, c) do { _Pragma("unroll") for (int kb = 0; kb < 4; ++kb) { sv[kb] = (f32x4){sinit, sinit, sinit, sinit}; _Pragma("unroll") for (int ds = 0; ds < 2; ++ds) \
;                 sv[kb] = __builtin_amdgcn_mfma_f32_16x16x32_bf16(kf[kb * 2 + ds], qf[c][ds], sv[kb], 0, 0, 0); } } while (0)
; #define ATT_PVW(c, lo_, hi_, eb0) do { ATT_W4(12, lo_, hi_, 0); ATT_PV1(c, lo_, hi_, eb0, 0); ATT_W4(8, lo_, hi_, 1); ATT_PV1(c, lo_, hi_, eb0, 1); \
;                 ATT_W4(4, lo_, hi_, 2); ATT_PV1(c, lo_, hi_, eb0, 2); ATT_W4(0, lo_, hi_, 3); ATT_PV1(c, lo_, hi_, eb0, 3); } while (0)
; #define ATT_SB __builtin_amdgcn_sched_barrier(0)
; template <bool DIFF>
; __device__ __forceinline__ void attn_item(LAS unsigned char* lds, const bf16_t* Z, bf16_t* MIX, int b, int h, int t, float lam, float shift, const float* gain, int tid, int wid, int lane) {
;     ...
;             ATT_KREAD(kfA, 0); ATT_SB;
;             if (DIFF) { ATT_KREAD(kfB, NC - 1); ATT_SMMA(s0, kfA, 0); ATT_SB;
;                         ATT_VISSUE(vAl, vAh, 0); ATT_SMMA(s1, kfB, NC - 1); ATT_SOFT(s0, 0); ATT_SB;
;                         ATT_SOFT(s1, NC - 1); ATT_PVW(0, vAl, vAh, 0); ATT_SB;
.Ldx_nd0:
	s_waitcnt lgkmcnt(0)
	v_mfma_f32_16x16x32_bf16 v[188:191], v[84:87], v[80:83], v[0:3]
	v_mfma_f32_16x16x32_bf16 v[192:195], v[88:91], v[80:83], v[0:3]
	v_mfma_f32_16x16x32_bf16 v[196:199], v[100:103], v[80:83], v[0:3]
	v_mfma_f32_16x16x32_bf16 v[200:203], v[104:107], v[80:83], v[0:3]
	v_mfma_f32_16x16x32_bf16 v[188:191], v[92:95], v[76:79], v[188:191]
	v_mfma_f32_16x16x32_bf16 v[192:195], v[96:99], v[76:79], v[192:195]
	v_mfma_f32_16x16x32_bf16 v[196:199], v[108:111], v[76:79], v[196:199]
	v_mfma_f32_16x16x32_bf16 v[200:203], v[112:115], v[76:79], v[200:203]
	ds_read_b128 v[84:87], v116 offset:8192
	ds_read_b128 v[88:91], v116 offset:10240
	ds_read_b128 v[92:95], v117 offset:8192
	ds_read_b128 v[96:99], v117 offset:10240
	ds_read_b128 v[100:103], v116 offset:12288
	ds_read_b128 v[104:107], v116 offset:14336
	ds_read_b128 v[108:111], v117 offset:12288
	ds_read_b128 v[112:115], v117 offset:14336
	s_waitcnt lgkmcnt(0)
	v_mfma_f32_16x16x32_bf16 v[204:207], v[84:87], v[72:75], v[0:3]
	v_exp_f32_e32 v188, v188
	v_exp_f32_e32 v189, v189
	v_mfma_f32_16x16x32_bf16 v[208:211], v[88:91], v[72:75], v[0:3]
	v_exp_f32_e32 v190, v190
	v_exp_f32_e32 v191, v191
	v_mfma_f32_16x16x32_bf16 v[212:215], v[100:103], v[72:75], v[0:3]
	v_exp_f32_e32 v192, v192
	v_exp_f32_e32 v193, v193
	v_mfma_f32_16x16x32_bf16 v[216:219], v[104:107], v[72:75], v[0:3]
	v_exp_f32_e32 v194, v194
	v_exp_f32_e32 v195, v195
	v_mfma_f32_16x16x32_bf16 v[204:207], v[92:95], v[68:71], v[204:207]
	v_exp_f32_e32 v196, v196
	v_exp_f32_e32 v197, v197
	v_mfma_f32_16x16x32_bf16 v[208:211], v[96:99], v[68:71], v[208:211]
	v_exp_f32_e32 v198, v198
	v_exp_f32_e32 v199, v199
	v_mfma_f32_16x16x32_bf16 v[212:215], v[108:111], v[68:71], v[212:215]
	v_exp_f32_e32 v200, v200
	v_exp_f32_e32 v201, v201
	v_mfma_f32_16x16x32_bf16 v[216:219], v[112:115], v[68:71], v[216:219]
	v_exp_f32_e32 v202, v202
	v_exp_f32_e32 v203, v203
	v_add_u32_e32 v118, s0, v143
	v_add_u32_e32 v120, v118, v142
	v_add_u32_e32 v121, v118, v141
	v_add_u32_e32 v122, v118, v140
	v_add_u32_e32 v123, v118, v139
	ds_read_b64_tr_b16 v[148:149], v120
	ds_read_b64_tr_b16 v[150:151], v120 offset:4096
	ds_read_b64_tr_b16 v[152:153], v120 offset:8192
	ds_read_b64_tr_b16 v[154:155], v120 offset:12288
	ds_read_b64_tr_b16 v[156:157], v121
	ds_read_b64_tr_b16 v[158:159], v121 offset:4096
	ds_read_b64_tr_b16 v[160:161], v121 offset:8192
	ds_read_b64_tr_b16 v[162:163], v121 offset:12288
	ds_read_b64_tr_b16 v[164:165], v122
	ds_read_b64_tr_b16 v[166:167], v122 offset:4096
	ds_read_b64_tr_b16 v[168:169], v122 offset:8192
	ds_read_b64_tr_b16 v[170:171], v122 offset:12288
	ds_read_b64_tr_b16 v[172:173], v123
	ds_read_b64_tr_b16 v[174:175], v123 offset:4096
	ds_read_b64_tr_b16 v[176:177], v123 offset:8192
	ds_read_b64_tr_b16 v[178:179], v123 offset:12288
	v_exp_f32_e32 v204, v204
	v_exp_f32_e32 v205, v205
	v_exp_f32_e32 v206, v206
	v_exp_f32_e32 v207, v207
	v_exp_f32_e32 v208, v208
	v_exp_f32_e32 v209, v209
	v_exp_f32_e32 v210, v210
	v_exp_f32_e32 v211, v211
	v_exp_f32_e32 v212, v212
	v_exp_f32_e32 v213, v213
	v_exp_f32_e32 v214, v214
	v_exp_f32_e32 v215, v215
	v_exp_f32_e32 v216, v216
	v_exp_f32_e32 v217, v217
	v_exp_f32_e32 v218, v218
	v_exp_f32_e32 v219, v219
	v_cvt_pk_bf16_f32 v220, v188, v189
	v_cvt_pk_bf16_f32 v221, v190, v191
	v_cvt_pk_bf16_f32 v222, v192, v193
	v_cvt_pk_bf16_f32 v223, v194, v195
	v_cvt_pk_bf16_f32 v224, v196, v197
	v_cvt_pk_bf16_f32 v225, v198, v199
	v_cvt_pk_bf16_f32 v226, v200, v201
	v_cvt_pk_bf16_f32 v227, v202, v203
	v_cvt_pk_bf16_f32 v228, v204, v205
	v_cvt_pk_bf16_f32 v229, v206, v207
	v_cvt_pk_bf16_f32 v230, v208, v209
	v_cvt_pk_bf16_f32 v231, v210, v211
	v_cvt_pk_bf16_f32 v232, v212, v213
	v_cvt_pk_bf16_f32 v233, v214, v215
	v_cvt_pk_bf16_f32 v234, v216, v217
	v_cvt_pk_bf16_f32 v235, v218, v219
	s_cmp_eq_u32 s70, 0
	s_cbranch_scc1 .Ldx_w00
	s_waitcnt vmcnt(4)
	s_branch .Ldx_b0

; #define ATT_KREAD(dst, c) do { _Pragma("unroll") for (int kb = 0; kb < 4; ++kb) _Pragma("unroll") for (int ds = 0; ds < 2; ++ds) \
;                 dst[kb * 2 + ds] = *(const LAS bf16x8*)(bp + (c) * 8192 + kb * 2048 + kfo + (((unsigned)(4 * ds + quad) ^ ksw) * 16)); } while (0)
; #define ATT_SMMA(sv, kf, c) do { _Pragma("unroll") for (int kb = 0; kb < 4; ++kb) { sv[kb] = (f32x4){sinit, sinit, sinit, sinit}; _Pragma("unroll") for (int ds = 0; ds < 2; ++ds) \
;                 sv[kb] = __builtin_amdgcn_mfma_f32_16x16x32_bf16(kf[kb * 2 + ds], qf[c][ds], sv[kb], 0, 0, 0); } } while (0)
; #define ATT_PV(c, lo_, hi_, eb0) do { _Pragma("unroll") for (int e = 0; e < 4; ++e) _Pragma("unroll") for (int ks = 0; ks < 2; ++ks) \
;                 O[c][(eb0) + e] = __builtin_amdgcn_mfma_f32_16x16x32_bf16(__builtin_shufflevector(lo_[e * 2 + ks], hi_[e * 2 + ks], 0, 1, 2, 3, 4, 5, 6, 7), P[c][ks], O[c][(eb0) + e], 0, 0, 0); } while (0)
; #define ATT_PVW(c, lo_, hi_, eb0) do { ATT_W4(12, lo_, hi_, 0); ATT_PV1(c, lo_, hi_, eb0, 0); ATT_W4(8, lo_, hi_, 1); ATT_PV1(c, lo_, hi_, eb0, 1); \
;                 ATT_W4(4, lo_, hi_, 2); ATT_PV1(c, lo_, hi_, eb0, 2); ATT_W4(0, lo_, hi_, 3); ATT_PV1(c, lo_, hi_, eb0, 3); } while (0)
; #define ATT_SB __builtin_amdgcn_sched_barrier(0)
; template <bool DIFF>
; __device__ __forceinline__ void attn_item(LAS unsigned char* lds, const bf16_t* Z, bf16_t* MIX, int b, int h, int t, float lam, float shift, const float* gain, int tid, int wid, int lane) {
;     ...
;             ATT_KREAD(kfA, 0); ATT_SB;
;             if (DIFF) { ATT_KREAD(kfB, NC - 1); ATT_SMMA(s0, kfA, 0); ATT_SB;
;                         ATT_VISSUE(vAl, vAh, 0); ATT_SMMA(s1, kfB, NC - 1); ATT_SOFT(s0, 0); ATT_SB;
;                         ATT_SOFT(s1, NC - 1); ATT_PVW(0, vAl, vAh, 0); ATT_SB;
;                         ATT_VISSUE(vBl, vBh, 4); ATT_PV(NC - 1, vAl, vAh, 0); ATT_SB;
;                         ATT_PVW(0, vBl, vBh, 4); ATT_PV(NC - 1, vBl, vBh, 4); ATT_SB; }
.Ldx_loop:
	s_and_b32 s0, s15, 3
	s_lshl_b32 s0, s0, 15
	s_add_i32 s1, s15, 3
	s_and_b32 s1, s1, 3
	s_lshl_b32 s1, s1, 15
	s_add_i32 s16, s15, 2
	s_and_b32 s16, s16, 3
	s_lshl_b32 s16, s16, 15
	s_add_i32 s16, s16, s90
	s_cmp_gt_u32 s15, s83
	s_cbranch_scc1 .Ldx_pvo
	s_waitcnt lgkmcnt(0)
	v_add_u32_e32 v119, s0, v144
	v_add_u32_e32 v116, v119, v145
	v_add_u32_e32 v117, v119, v146
	ds_read_b128 v[84:87], v116
	ds_read_b128 v[88:91], v116 offset:2048
	ds_read_b128 v[92:95], v117
	ds_read_b128 v[96:99], v117 offset:2048
	ds_read_b128 v[100:103], v116 offset:4096
	ds_read_b128 v[104:107], v116 offset:6144
	ds_read_b128 v[108:111], v117 offset:4096
	ds_read_b128 v[112:115], v117 offset:6144
	v_add_u32_e32 v118, s1, v143
	v_add_u32_e32 v120, v118, v138
	v_add_u32_e32 v121, v118, v137
	v_add_u32_e32 v122, v118, v136
	v_add_u32_e32 v123, v118, v129
	v_mfma_f32_16x16x32_bf16 v[64:67], v[148:151], v[220:223], v[64:67]
	v_add_f32_e32 v131, v131, v188
	v_add_f32_e32 v131, v131, v189
	v_mfma_f32_16x16x32_bf16 v[60:63], v[156:159], v[220:223], v[60:63]
	v_add_f32_e32 v131, v131, v190
	v_add_f32_e32 v131, v131, v191
	v_mfma_f32_16x16x32_bf16 v[56:59], v[148:151], v[228:231], v[56:59]
	v_add_f32_e32 v131, v131, v192
	v_add_f32_e32 v131, v131, v193
	v_mfma_f32_16x16x32_bf16 v[52:55], v[156:159], v[228:231], v[52:55]
	v_add_f32_e32 v131, v131, v194
	v_add_f32_e32 v131, v131, v195
	v_mfma_f32_16x16x32_bf16 v[64:67], v[152:155], v[224:227], v[64:67]
	v_add_f32_e32 v131, v131, v196
	v_add_f32_e32 v131, v131, v197
	v_mfma_f32_16x16x32_bf16 v[60:63], v[160:163], v[224:227], v[60:63]
	v_add_f32_e32 v131, v131, v198
	v_add_f32_e32 v131, v131, v199
	v_mfma_f32_16x16x32_bf16 v[56:59], v[152:155], v[232:235], v[56:59]
	v_add_f32_e32 v131, v131, v200
	v_add_f32_e32 v131, v131, v201
	v_mfma_f32_16x16x32_bf16 v[52:55], v[160:163], v[232:235], v[52:55]
	v_add_f32_e32 v131, v131, v202
	v_add_f32_e32 v131, v131, v203
	ds_read_b64_tr_b16 v[148:149], v120
	ds_read_b64_tr_b16 v[150:151], v120 offset:4096
	ds_read_b64_tr_b16 v[152:153], v120 offset:8192
	ds_read_b64_tr_b16 v[154:155], v120 offset:12288
	ds_read_b64_tr_b16 v[156:157], v121
	ds_read_b64_tr_b16 v[158:159], v121 offset:4096
	ds_read_b64_tr_b16 v[160:161], v121 offset:8192
	ds_read_b64_tr_b16 v[162:163], v121 offset:12288
	v_mfma_f32_16x16x32_bf16 v[48:51], v[164:167], v[220:223], v[48:51]
	v_add_f32_e32 v130, v130, v204
	v_add_f32_e32 v130, v130, v205
	v_mfma_f32_16x16x32_bf16 v[40:43], v[172:175], v[220:223], v[40:43]
	v_add_f32_e32 v130, v130, v206
	v_add_f32_e32 v130, v130, v207
	v_mfma_f32_16x16x32_bf16 v[44:47], v[164:167], v[228:231], v[44:47]
	v_add_f32_e32 v130, v130, v208
	v_add_f32_e32 v130, v130, v209
	v_mfma_f32_16x16x32_bf16 v[36:39], v[172:175], v[228:231], v[36:39]
	v_add_f32_e32 v130, v130, v210
	v_add_f32_e32 v130, v130, v211
	v_mfma_f32_16x16x32_bf16 v[48:51], v[168:171], v[224:227], v[48:51]
	v_add_f32_e32 v130, v130, v212
	v_add_f32_e32 v130, v130, v213
	v_mfma_f32_16x16x32_bf16 v[40:43], v[176:179], v[224:227], v[40:43]
	v_add_f32_e32 v130, v130, v214
	v_add_f32_e32 v130, v130, v215
	v_mfma_f32_16x16x32_bf16 v[44:47], v[168:171], v[232:235], v[44:47]
	v_add_f32_e32 v130, v130, v216
	v_add_f32_e32 v130, v130, v217
	v_mfma_f32_16x16x32_bf16 v[36:39], v[176:179], v[232:235], v[36:39]
	v_add_f32_e32 v130, v130, v218
	v_add_f32_e32 v130, v130, v219
	ds_read_b64_tr_b16 v[164:165], v122
	ds_read_b64_tr_b16 v[166:167], v122 offset:4096
	ds_read_b64_tr_b16 v[168:169], v122 offset:8192
	ds_read_b64_tr_b16 v[170:171], v122 offset:12288
	ds_read_b64_tr_b16 v[172:173], v123
	ds_read_b64_tr_b16 v[174:175], v123 offset:4096
	ds_read_b64_tr_b16 v[176:177], v123 offset:8192
	ds_read_b64_tr_b16 v[178:179], v123 offset:12288
	s_cmp_ge_u32 s15, s70
	s_cbranch_scc1 .Ldx_nd
	s_add_u32 s18, s4, 0xfffff800
	s_addc_u32 s19, s5, -1
	s_add_u32 s22, s18, 0x80
	s_addc_u32 s23, s19, 0
	s_add_u32 s24, s4, 0x70000
	s_addc_u32 s25, s5, 0
	s_mov_b32 m0, s16
	s_nop 0
	global_load_lds_dwordx4 v180, s[18:19]
	s_add_i32 m0, s16, 0x2000
	s_nop 0
	global_load_lds_dwordx4 v180, s[22:23]
	s_add_i32 m0, s16, 0x4000
	s_nop 0
	global_load_lds_dwordx4 v132, s[4:5]
	s_add_i32 m0, s16, 0x6000
	s_nop 0
	global_load_lds_dwordx4 v132, s[24:25]
	s_add_u32 s4, s4, 0xe0000
	s_addc_u32 s5, s5, 0
; #define ATT_KREAD(dst, c) do { _Pragma("unroll") for (int kb = 0; kb < 4; ++kb) _Pragma("unroll") for (int ds = 0; ds < 2; ++ds) \
;                 dst[kb * 2 + ds] = *(const LAS bf16x8*)(bp + (c) * 8192 + kb * 2048 + kfo + (((unsigned)(4 * ds + quad) ^ ksw) * 16)); } while (0)
; #define ATT_SMMA(sv, kf, c) do { _Pragma("unroll") for (int kb = 0; kb < 4; ++kb) { sv[kb] = (f32x4){sinit, sinit, sinit, sinit}; _Pragma("unroll") for (int ds = 0; ds < 2; ++ds) \
;                 sv[kb] = __builtin_amdgcn_mfma_f32_16x16x32_bf16(kf[kb * 2 + ds], qf[c][ds], sv[kb], 0, 0, 0); } } while (0)
; #define ATT_PV(c, lo_, hi_, eb0) do { _Pragma("unroll") for (int e = 0; e < 4; ++e) _Pragma("unroll") for (int ks = 0; ks < 2; ++ks) \
;                 O[c][(eb0) + e] = __builtin_amdgcn_mfma_f32_16x16x32_bf16(__builtin_shufflevector(lo_[e * 2 + ks], hi_[e * 2 + ks], 0, 1, 2, 3, 4, 5, 6, 7), P[c][ks], O[c][(eb0) + e], 0, 0, 0); } while (0)
; #define ATT_PVW(c, lo_, hi_, eb0) do { ATT_W4(12, lo_, hi_, 0); ATT_PV1(c, lo_, hi_, eb0, 0); ATT_W4(8, lo_, hi_, 1); ATT_PV1(c, lo_, hi_, eb0, 1); \
;                 ATT_W4(4, lo_, hi_, 2); ATT_PV1(c, lo_, hi_, eb0, 2); ATT_W4(0, lo_, hi_, 3); ATT_PV1(c, lo_, hi_, eb0, 3); } while (0)
; #define ATT_SB __builtin_amdgcn_sched_barrier(0)
; template <bool DIFF>
; __device__ __forceinline__ void attn_item(LAS unsigned char* lds, const bf16_t* Z, bf16_t* MIX, int b, int h, int t, float lam, float shift, const float* gain, int tid, int wid, int lane) {
;     ...
;             ATT_KREAD(kfA, 0); ATT_SB;
;             if (DIFF) { ATT_KREAD(kfB, NC - 1); ATT_SMMA(s0, kfA, 0); ATT_SB;
;                         ATT_VISSUE(vAl, vAh, 0); ATT_SMMA(s1, kfB, NC - 1); ATT_SOFT(s0, 0); ATT_SB;
;                         ATT_SOFT(s1, NC - 1); ATT_PVW(0, vAl, vAh, 0); ATT_SB;
;                         ATT_VISSUE(vBl, vBh, 4); ATT_PV(NC - 1, vAl, vAh, 0); ATT_SB;
;                         ATT_PVW(0, vBl, vBh, 4); ATT_PV(NC - 1, vBl, vBh, 4); ATT_SB; }
.Ldx_nd:
	s_waitcnt lgkmcnt(15)
	v_mfma_f32_16x16x32_bf16 v[188:191], v[84:87], v[80:83], v[0:3]
	v_mfma_f32_16x16x32_bf16 v[192:195], v[88:91], v[80:83], v[0:3]
	v_mfma_f32_16x16x32_bf16 v[196:199], v[100:103], v[80:83], v[0:3]
	v_mfma_f32_16x16x32_bf16 v[200:203], v[104:107], v[80:83], v[0:3]
	v_mfma_f32_16x16x32_bf16 v[188:191], v[92:95], v[76:79], v[188:191]
	v_mfma_f32_16x16x32_bf16 v[192:195], v[96:99], v[76:79], v[192:195]
	v_mfma_f32_16x16x32_bf16 v[196:199], v[108:111], v[76:79], v[196:199]
	v_mfma_f32_16x16x32_bf16 v[200:203], v[112:115], v[76:79], v[200:203]
	ds_read_b128 v[84:87], v116 offset:8192
	ds_read_b128 v[88:91], v116 offset:10240
	ds_read_b128 v[92:95], v117 offset:8192
	ds_read_b128 v[96:99], v117 offset:10240
	ds_read_b128 v[100:103], v116 offset:12288
	ds_read_b128 v[104:107], v116 offset:14336
	ds_read_b128 v[108:111], v117 offset:12288
	ds_read_b128 v[112:115], v117 offset:14336
	s_waitcnt lgkmcnt(15)
	v_mfma_f32_16x16x32_bf16 v[32:35], v[148:151], v[220:223], v[32:35]
	v_exp_f32_e32 v188, v188
	v_mfma_f32_16x16x32_bf16 v[24:27], v[156:159], v[220:223], v[24:27]
	v_exp_f32_e32 v189, v189
	v_mfma_f32_16x16x32_bf16 v[28:31], v[148:151], v[228:231], v[28:31]
	v_exp_f32_e32 v190, v190
	v_mfma_f32_16x16x32_bf16 v[20:23], v[156:159], v[228:231], v[20:23]
	v_exp_f32_e32 v191, v191
	v_mfma_f32_16x16x32_bf16 v[32:35], v[152:155], v[224:227], v[32:35]
	v_exp_f32_e32 v192, v192
	v_mfma_f32_16x16x32_bf16 v[24:27], v[160:163], v[224:227], v[24:27]
	v_exp_f32_e32 v193, v193
	v_mfma_f32_16x16x32_bf16 v[28:31], v[152:155], v[232:235], v[28:31]
	v_exp_f32_e32 v194, v194
	v_mfma_f32_16x16x32_bf16 v[20:23], v[160:163], v[232:235], v[20:23]
	v_exp_f32_e32 v195, v195
	s_waitcnt lgkmcnt(8)
	v_mfma_f32_16x16x32_bf16 v[16:19], v[164:167], v[220:223], v[16:19]
	v_exp_f32_e32 v196, v196
	v_mfma_f32_16x16x32_bf16 v[8:11], v[172:175], v[220:223], v[8:11]
	v_exp_f32_e32 v197, v197
	v_mfma_f32_16x16x32_bf16 v[12:15], v[164:167], v[228:231], v[12:15]
	v_exp_f32_e32 v198, v198
	v_mfma_f32_16x16x32_bf16 v[4:7], v[172:175], v[228:231], v[4:7]
	v_exp_f32_e32 v199, v199
	v_mfma_f32_16x16x32_bf16 v[16:19], v[168:171], v[224:227], v[16:19]
	v_exp_f32_e32 v200, v200
	v_mfma_f32_16x16x32_bf16 v[8:11], v[176:179], v[224:227], v[8:11]
	v_exp_f32_e32 v201, v201
	v_mfma_f32_16x16x32_bf16 v[12:15], v[168:171], v[232:235], v[12:15]
	v_exp_f32_e32 v202, v202
	v_mfma_f32_16x16x32_bf16 v[4:7], v[176:179], v[232:235], v[4:7]
	v_exp_f32_e32 v203, v203
	s_waitcnt lgkmcnt(0)
	v_mfma_f32_16x16x32_bf16 v[204:207], v[84:87], v[72:75], v[0:3]
	v_mfma_f32_16x16x32_bf16 v[208:211], v[88:91], v[72:75], v[0:3]
	v_mfma_f32_16x16x32_bf16 v[212:215], v[100:103], v[72:75], v[0:3]
	v_mfma_f32_16x16x32_bf16 v[216:219], v[104:107], v[72:75], v[0:3]
	v_mfma_f32_16x16x32_bf16 v[204:207], v[92:95], v[68:71], v[204:207]
	v_cvt_pk_bf16_f32 v220, v188, v189
	v_cvt_pk_bf16_f32 v221, v190, v191
	v_mfma_f32_16x16x32_bf16 v[208:211], v[96:99], v[68:71], v[208:211]
	v_cvt_pk_bf16_f32 v222, v192, v193
	v_cvt_pk_bf16_f32 v223, v194, v195
	v_mfma_f32_16x16x32_bf16 v[212:215], v[108:111], v[68:71], v[212:215]
	v_cvt_pk_bf16_f32 v224, v196, v197
	v_cvt_pk_bf16_f32 v225, v198, v199
	v_mfma_f32_16x16x32_bf16 v[216:219], v[112:115], v[68:71], v[216:219]
	v_cvt_pk_bf16_f32 v226, v200, v201
	v_cvt_pk_bf16_f32 v227, v202, v203
	v_add_u32_e32 v118, s0, v143
	v_add_u32_e32 v120, v118, v142
	v_add_u32_e32 v121, v118, v141
	v_add_u32_e32 v122, v118, v140
	v_add_u32_e32 v123, v118, v139
	ds_read_b64_tr_b16 v[148:149], v120
	ds_read_b64_tr_b16 v[150:151], v120 offset:4096
	ds_read_b64_tr_b16 v[152:153], v120 offset:8192
	ds_read_b64_tr_b16 v[154:155], v120 offset:12288
	ds_read_b64_tr_b16 v[156:157], v121
	ds_read_b64_tr_b16 v[158:159], v121 offset:4096
	ds_read_b64_tr_b16 v[160:161], v121 offset:8192
	ds_read_b64_tr_b16 v[162:163], v121 offset:12288
	ds_read_b64_tr_b16 v[164:165], v122
	ds_read_b64_tr_b16 v[166:167], v122 offset:4096
	ds_read_b64_tr_b16 v[168:169], v122 offset:8192
	ds_read_b64_tr_b16 v[170:171], v122 offset:12288
	ds_read_b64_tr_b16 v[172:173], v123
	ds_read_b64_tr_b16 v[174:175], v123 offset:4096
	ds_read_b64_tr_b16 v[176:177], v123 offset:8192
	ds_read_b64_tr_b16 v[178:179], v123 offset:12288
	v_exp_f32_e32 v204, v204
	v_exp_f32_e32 v205, v205
	v_exp_f32_e32 v206, v206
	v_exp_f32_e32 v207, v207
	v_exp_f32_e32 v208, v208
	v_exp_f32_e32 v209, v209
	v_exp_f32_e32 v210, v210
	v_exp_f32_e32 v211, v211
	v_exp_f32_e32 v212, v212
	v_exp_f32_e32 v213, v213
	v_exp_f32_e32 v214, v214
	v_exp_f32_e32 v215, v215
	v_exp_f32_e32 v216, v216
	v_exp_f32_e32 v217, v217
	v_exp_f32_e32 v218, v218
	v_exp_f32_e32 v219, v219
	v_cvt_pk_bf16_f32 v228, v204, v205
	v_cvt_pk_bf16_f32 v229, v206, v207
	v_cvt_pk_bf16_f32 v230, v208, v209
	v_cvt_pk_bf16_f32 v231, v210, v211
	v_cvt_pk_bf16_f32 v232, v212, v213
	v_cvt_pk_bf16_f32 v233, v214, v215
	v_cvt_pk_bf16_f32 v234, v216, v217
	v_cvt_pk_bf16_f32 v235, v218, v219
	s_branch .Ldx_end
; #define ATT_KREAD(dst, c) do { _Pragma("unroll") for (int kb = 0; kb < 4; ++kb) _Pragma("unroll") for (int ds = 0; ds < 2; ++ds) \
;                 dst[kb * 2 + ds] = *(const LAS bf16x8*)(bp + (c) * 8192 + kb * 2048 + kfo + (((unsigned)(4 * ds + quad) ^ ksw) * 16)); } while (0)
; #define ATT_SMMA(sv, kf, c) do { _Pragma("unroll") for (int kb = 0; kb < 4; ++kb) { sv[kb] = (f32x4){sinit, sinit, sinit, sinit}; _Pragma("unroll") for (int ds = 0; ds < 2; ++ds) \
;                 sv[kb] = __builtin_amdgcn_mfma_f32_16x16x32_bf16(kf[kb * 2 + ds], qf[c][ds], sv[kb], 0, 0, 0); } } while (0)
; #define ATT_PV(c, lo_, hi_, eb0) do { _Pragma("unroll") for (int e = 0; e < 4; ++e) _Pragma("unroll") for (int ks = 0; ks < 2; ++ks) \
;                 O[c][(eb0) + e] = __builtin_amdgcn_mfma_f32_16x16x32_bf16(__builtin_shufflevector(lo_[e * 2 + ks], hi_[e * 2 + ks], 0, 1, 2, 3, 4, 5, 6, 7), P[c][ks], O[c][(eb0) + e], 0, 0, 0); } while (0)
; #define ATT_PVW(c, lo_, hi_, eb0) do { ATT_W4(12, lo_, hi_, 0); ATT_PV1(c, lo_, hi_, eb0, 0); ATT_W4(8, lo_, hi_, 1); ATT_PV1(c, lo_, hi_, eb0, 1); \
;                 ATT_W4(4, lo_, hi_, 2); ATT_PV1(c, lo_, hi_, eb0, 2); ATT_W4(0, lo_, hi_, 3); ATT_PV1(c, lo_, hi_, eb0, 3); } while (0)
; #define ATT_SB __builtin_amdgcn_sched_barrier(0)
; template <bool DIFF>
; __device__ __forceinline__ void attn_item(LAS unsigned char* lds, const bf16_t* Z, bf16_t* MIX, int b, int h, int t, float lam, float shift, const float* gain, int tid, int wid, int lane) {
;     ...
;             ATT_KREAD(kfA, 0); ATT_SB;
;             if (DIFF) { ATT_KREAD(kfB, NC - 1); ATT_SMMA(s0, kfA, 0); ATT_SB;
;                         ATT_VISSUE(vAl, vAh, 0); ATT_SMMA(s1, kfB, NC - 1); ATT_SOFT(s0, 0); ATT_SB;
;                         ATT_SOFT(s1, NC - 1); ATT_PVW(0, vAl, vAh, 0); ATT_SB;
;                         ATT_VISSUE(vBl, vBh, 4); ATT_PV(NC - 1, vAl, vAh, 0); ATT_SB;
;                         ATT_PVW(0, vBl, vBh, 4); ATT_PV(NC - 1, vBl, vBh, 4); ATT_SB; }
.Ldx_pvo:
	s_waitcnt lgkmcnt(0)
	v_add_u32_e32 v118, s1, v143
	v_add_u32_e32 v120, v118, v138
	v_add_u32_e32 v121, v118, v137
	v_add_u32_e32 v122, v118, v136
	v_add_u32_e32 v123, v118, v129
	v_mfma_f32_16x16x32_bf16 v[64:67], v[148:151], v[220:223], v[64:67]
	v_add_f32_e32 v131, v131, v188
	v_add_f32_e32 v131, v131, v189
	v_mfma_f32_16x16x32_bf16 v[60:63], v[156:159], v[220:223], v[60:63]
	v_add_f32_e32 v131, v131, v190
	v_add_f32_e32 v131, v131, v191
	v_mfma_f32_16x16x32_bf16 v[56:59], v[148:151], v[228:231], v[56:59]
	v_add_f32_e32 v131, v131, v192
	v_add_f32_e32 v131, v131, v193
	v_mfma_f32_16x16x32_bf16 v[52:55], v[156:159], v[228:231], v[52:55]
	v_add_f32_e32 v131, v131, v194
	v_add_f32_e32 v131, v131, v195
	v_mfma_f32_16x16x32_bf16 v[64:67], v[152:155], v[224:227], v[64:67]
	v_add_f32_e32 v131, v131, v196
	v_add_f32_e32 v131, v131, v197
	v_mfma_f32_16x16x32_bf16 v[60:63], v[160:163], v[224:227], v[60:63]
	v_add_f32_e32 v131, v131, v198
	v_add_f32_e32 v131, v131, v199
	v_mfma_f32_16x16x32_bf16 v[56:59], v[152:155], v[232:235], v[56:59]
	v_add_f32_e32 v131, v131, v200
	v_add_f32_e32 v131, v131, v201
	v_mfma_f32_16x16x32_bf16 v[52:55], v[160:163], v[232:235], v[52:55]
	v_add_f32_e32 v131, v131, v202
	v_add_f32_e32 v131, v131, v203
	ds_read_b64_tr_b16 v[148:149], v120
	ds_read_b64_tr_b16 v[150:151], v120 offset:4096
	ds_read_b64_tr_b16 v[152:153], v120 offset:8192
	ds_read_b64_tr_b16 v[154:155], v120 offset:12288
	ds_read_b64_tr_b16 v[156:157], v121
	ds_read_b64_tr_b16 v[158:159], v121 offset:4096
	ds_read_b64_tr_b16 v[160:161], v121 offset:8192
	ds_read_b64_tr_b16 v[162:163], v121 offset:12288
	v_mfma_f32_16x16x32_bf16 v[48:51], v[164:167], v[220:223], v[48:51]
	v_add_f32_e32 v130, v130, v204
	v_add_f32_e32 v130, v130, v205
	v_mfma_f32_16x16x32_bf16 v[40:43], v[172:175], v[220:223], v[40:43]
	v_add_f32_e32 v130, v130, v206
	v_add_f32_e32 v130, v130, v207
	v_mfma_f32_16x16x32_bf16 v[44:47], v[164:167], v[228:231], v[44:47]
	v_add_f32_e32 v130, v130, v208
	v_add_f32_e32 v130, v130, v209
	v_mfma_f32_16x16x32_bf16 v[36:39], v[172:175], v[228:231], v[36:39]
	v_add_f32_e32 v130, v130, v210
	v_add_f32_e32 v130, v130, v211
	v_mfma_f32_16x16x32_bf16 v[48:51], v[168:171], v[224:227], v[48:51]
	v_add_f32_e32 v130, v130, v212
	v_add_f32_e32 v130, v130, v213
	v_mfma_f32_16x16x32_bf16 v[40:43], v[176:179], v[224:227], v[40:43]
	v_add_f32_e32 v130, v130, v214
	v_add_f32_e32 v130, v130, v215
	v_mfma_f32_16x16x32_bf16 v[44:47], v[168:171], v[232:235], v[44:47]
	v_add_f32_e32 v130, v130, v216
	v_add_f32_e32 v130, v130, v217
	v_mfma_f32_16x16x32_bf16 v[36:39], v[176:179], v[232:235], v[36:39]
	v_add_f32_e32 v130, v130, v218
	v_add_f32_e32 v130, v130, v219
	ds_read_b64_tr_b16 v[164:165], v122
	ds_read_b64_tr_b16 v[166:167], v122 offset:4096
	ds_read_b64_tr_b16 v[168:169], v122 offset:8192
	ds_read_b64_tr_b16 v[170:171], v122 offset:12288
	ds_read_b64_tr_b16 v[172:173], v123
	ds_read_b64_tr_b16 v[174:175], v123 offset:4096
	ds_read_b64_tr_b16 v[176:177], v123 offset:8192
	ds_read_b64_tr_b16 v[178:179], v123 offset:12288
	s_waitcnt lgkmcnt(8)
	v_mfma_f32_16x16x32_bf16 v[32:35], v[148:151], v[220:223], v[32:35]
	v_mfma_f32_16x16x32_bf16 v[24:27], v[156:159], v[220:223], v[24:27]
	v_mfma_f32_16x16x32_bf16 v[28:31], v[148:151], v[228:231], v[28:31]
	v_mfma_f32_16x16x32_bf16 v[20:23], v[156:159], v[228:231], v[20:23]
	v_mfma_f32_16x16x32_bf16 v[32:35], v[152:155], v[224:227], v[32:35]
	v_mfma_f32_16x16x32_bf16 v[24:27], v[160:163], v[224:227], v[24:27]
	v_mfma_f32_16x16x32_bf16 v[28:31], v[152:155], v[232:235], v[28:31]
	v_mfma_f32_16x16x32_bf16 v[20:23], v[160:163], v[232:235], v[20:23]
	s_waitcnt lgkmcnt(0)
	v_mfma_f32_16x16x32_bf16 v[16:19], v[164:167], v[220:223], v[16:19]
	v_mfma_f32_16x16x32_bf16 v[8:11], v[172:175], v[220:223], v[8:11]
	v_mfma_f32_16x16x32_bf16 v[12:15], v[164:167], v[228:231], v[12:15]
	v_mfma_f32_16x16x32_bf16 v[4:7], v[172:175], v[228:231], v[4:7]
	v_mfma_f32_16x16x32_bf16 v[16:19], v[168:171], v[224:227], v[16:19]
	v_mfma_f32_16x16x32_bf16 v[8:11], v[176:179], v[224:227], v[8:11]
	v_mfma_f32_16x16x32_bf16 v[12:15], v[168:171], v[232:235], v[12:15]
	v_mfma_f32_16x16x32_bf16 v[4:7], v[176:179], v[232:235], v[4:7]

; #define ATT_WAITBAR_ALL() asm volatile("s_waitcnt vmcnt(0) lgkmcnt(0)\n\ts_barrier" ::: "memory")
; #define ATT_WAITBAR_ONE() do { if (DIFF) asm volatile("s_waitcnt vmcnt(4) lgkmcnt(0)\n\ts_barrier" ::: "memory"); else asm volatile("s_waitcnt vmcnt(3) lgkmcnt(0)\n\ts_barrier" ::: "memory"); } while (0)
; #define ATT_KREAD(dst, c) do { _Pragma("unroll") for (int kb = 0; kb < 4; ++kb) _Pragma("unroll") for (int ds = 0; ds < 2; ++ds) \
;                 dst[kb * 2 + ds] = *(const LAS bf16x8*)(bp + (c) * 8192 + kb * 2048 + kfo + (((unsigned)(4 * ds + quad) ^ ksw) * 16)); } while (0)
; #define ATT_SMMA(sv, kf, c) do { _Pragma("unroll") for (int kb = 0; kb < 4; ++kb) { sv[kb] = (f32x4){sinit, sinit, sinit, sinit}; _Pragma("unroll") for (int ds = 0; ds < 2; ++ds) \
;                 sv[kb] = __builtin_amdgcn_mfma_f32_16x16x32_bf16(kf[kb * 2 + ds], qf[c][ds], sv[kb], 0, 0, 0); } } while (0)
; #define ATT_PV(c, lo_, hi_, eb0) do { _Pragma("unroll") for (int e = 0; e < 4; ++e) _Pragma("unroll") for (int ks = 0; ks < 2; ++ks) \
;                 O[c][(eb0) + e] = __builtin_amdgcn_mfma_f32_16x16x32_bf16(__builtin_shufflevector(lo_[e * 2 + ks], hi_[e * 2 + ks], 0, 1, 2, 3, 4, 5, 6, 7), P[c][ks], O[c][(eb0) + e], 0, 0, 0); } while (0)
; #define ATT_PVW(c, lo_, hi_, eb0) do { ATT_W4(12, lo_, hi_, 0); ATT_PV1(c, lo_, hi_, eb0, 0); ATT_W4(8, lo_, hi_, 1); ATT_PV1(c, lo_, hi_, eb0, 1); \
;                 ATT_W4(4, lo_, hi_, 2); ATT_PV1(c, lo_, hi_, eb0, 2); ATT_W4(0, lo_, hi_, 3); ATT_PV1(c, lo_, hi_, eb0, 3); } while (0)
; #define ATT_SB __builtin_amdgcn_sched_barrier(0)
; template <bool DIFF>
; __device__ __forceinline__ void attn_item(LAS unsigned char* lds, const bf16_t* Z, bf16_t* MIX, int b, int h, int t, float lam, float shift, const float* gain, int tid, int wid, int lane) {
;     ...
;             ATT_KREAD(kfA, 0); ATT_SB;
;             if (DIFF) { ATT_KREAD(kfB, NC - 1); ATT_SMMA(s0, kfA, 0); ATT_SB;
;                         ATT_VISSUE(vAl, vAh, 0); ATT_SMMA(s1, kfB, NC - 1); ATT_SOFT(s0, 0); ATT_SB;
;                         ATT_SOFT(s1, NC - 1); ATT_PVW(0, vAl, vAh, 0); ATT_SB;
;                         ATT_VISSUE(vBl, vBh, 4); ATT_PV(NC - 1, vAl, vAh, 0); ATT_SB;
;                         ATT_PVW(0, vBl, vBh, 4); ATT_PV(NC - 1, vBl, vBh, 4); ATT_SB; }
;     ...
;         if (kt + 1 < nkt) { if (more2) ATT_WAITBAR_ONE(); else ATT_WAITBAR_ALL(); }
.Ldx_exit:
	s_add_i32 s2, s70, 1
	s_cmp_le_u32 s2, s83
	s_cbranch_scc0 .Ldx_done
	s_and_b32 s1, s2, 3
	s_lshl_b32 s1, s1, 15
	s_waitcnt lgkmcnt(0)
	v_add_u32_e32 v118, s1, v143
	v_add_u32_e32 v120, v118, v138
	v_add_u32_e32 v121, v118, v137
	v_add_u32_e32 v122, v118, v136
	v_add_u32_e32 v123, v118, v129
	v_mfma_f32_16x16x32_bf16 v[64:67], v[148:151], v[220:223], v[64:67]
	v_add_f32_e32 v131, v131, v188
	v_add_f32_e32 v131, v131, v189
	v_mfma_f32_16x16x32_bf16 v[60:63], v[156:159], v[220:223], v[60:63]
	v_add_f32_e32 v131, v131, v190
	v_add_f32_e32 v131, v131, v191
	v_mfma_f32_16x16x32_bf16 v[56:59], v[148:151], v[228:231], v[56:59]
	v_add_f32_e32 v131, v131, v192
	v_add_f32_e32 v131, v131, v193
	v_mfma_f32_16x16x32_bf16 v[52:55], v[156:159], v[228:231], v[52:55]
	v_add_f32_e32 v131, v131, v194
	v_add_f32_e32 v131, v131, v195
	v_mfma_f32_16x16x32_bf16 v[64:67], v[152:155], v[224:227], v[64:67]
	v_add_f32_e32 v131, v131, v196
	v_add_f32_e32 v131, v131, v197
	v_mfma_f32_16x16x32_bf16 v[60:63], v[160:163], v[224:227], v[60:63]
	v_add_f32_e32 v131, v131, v198
	v_add_f32_e32 v131, v131, v199
	v_mfma_f32_16x16x32_bf16 v[56:59], v[152:155], v[232:235], v[56:59]
	v_add_f32_e32 v131, v131, v200
	v_add_f32_e32 v131, v131, v201
	v_mfma_f32_16x16x32_bf16 v[52:55], v[160:163], v[232:235], v[52:55]
	v_add_f32_e32 v131, v131, v202
	v_add_f32_e32 v131, v131, v203
	ds_read_b64_tr_b16 v[148:149], v120
	ds_read_b64_tr_b16 v[150:151], v120 offset:4096
	ds_read_b64_tr_b16 v[152:153], v120 offset:8192
	ds_read_b64_tr_b16 v[154:155], v120 offset:12288
	ds_read_b64_tr_b16 v[156:157], v121
	ds_read_b64_tr_b16 v[158:159], v121 offset:4096
	ds_read_b64_tr_b16 v[160:161], v121 offset:8192
	ds_read_b64_tr_b16 v[162:163], v121 offset:12288
	v_mfma_f32_16x16x32_bf16 v[48:51], v[164:167], v[220:223], v[48:51]
	v_add_f32_e32 v130, v130, v204
	v_add_f32_e32 v130, v130, v205
	v_mfma_f32_16x16x32_bf16 v[40:43], v[172:175], v[220:223], v[40:43]
	v_add_f32_e32 v130, v130, v206
	v_add_f32_e32 v130, v130, v207
	v_mfma_f32_16x16x32_bf16 v[44:47], v[164:167], v[228:231], v[44:47]
	v_add_f32_e32 v130, v130, v208
	v_add_f32_e32 v130, v130, v209
	v_mfma_f32_16x16x32_bf16 v[36:39], v[172:175], v[228:231], v[36:39]
	v_add_f32_e32 v130, v130, v210
	v_add_f32_e32 v130, v130, v211
	v_mfma_f32_16x16x32_bf16 v[48:51], v[168:171], v[224:227], v[48:51]
	v_add_f32_e32 v130, v130, v212
	v_add_f32_e32 v130, v130, v213
	v_mfma_f32_16x16x32_bf16 v[40:43], v[176:179], v[224:227], v[40:43]
	v_add_f32_e32 v130, v130, v214
	v_add_f32_e32 v130, v130, v215
	v_mfma_f32_16x16x32_bf16 v[44:47], v[168:171], v[232:235], v[44:47]
	v_add_f32_e32 v130, v130, v216
	v_add_f32_e32 v130, v130, v217
	v_mfma_f32_16x16x32_bf16 v[36:39], v[176:179], v[232:235], v[36:39]
	v_add_f32_e32 v130, v130, v218
	v_add_f32_e32 v130, v130, v219
	ds_read_b64_tr_b16 v[164:165], v122
	ds_read_b64_tr_b16 v[166:167], v122 offset:4096
	ds_read_b64_tr_b16 v[168:169], v122 offset:8192
	ds_read_b64_tr_b16 v[170:171], v122 offset:12288
	ds_read_b64_tr_b16 v[172:173], v123
	ds_read_b64_tr_b16 v[174:175], v123 offset:4096
	ds_read_b64_tr_b16 v[176:177], v123 offset:8192
	ds_read_b64_tr_b16 v[178:179], v123 offset:12288
	s_waitcnt lgkmcnt(8)
	v_mfma_f32_16x16x32_bf16 v[32:35], v[148:151], v[220:223], v[32:35]
	v_mfma_f32_16x16x32_bf16 v[24:27], v[156:159], v[220:223], v[24:27]
	v_mfma_f32_16x16x32_bf16 v[28:31], v[148:151], v[228:231], v[28:31]
	v_mfma_f32_16x16x32_bf16 v[20:23], v[156:159], v[228:231], v[20:23]
	v_mfma_f32_16x16x32_bf16 v[32:35], v[152:155], v[224:227], v[32:35]
	v_mfma_f32_16x16x32_bf16 v[24:27], v[160:163], v[224:227], v[24:27]
	v_mfma_f32_16x16x32_bf16 v[28:31], v[152:155], v[232:235], v[28:31]
	v_mfma_f32_16x16x32_bf16 v[20:23], v[160:163], v[232:235], v[20:23]
	s_waitcnt lgkmcnt(0)
	v_mfma_f32_16x16x32_bf16 v[16:19], v[164:167], v[220:223], v[16:19]
	v_mfma_f32_16x16x32_bf16 v[8:11], v[172:175], v[220:223], v[8:11]
	v_mfma_f32_16x16x32_bf16 v[12:15], v[164:167], v[228:231], v[12:15]
	v_mfma_f32_16x16x32_bf16 v[4:7], v[172:175], v[228:231], v[4:7]
	v_mfma_f32_16x16x32_bf16 v[16:19], v[168:171], v[224:227], v[16:19]
	v_mfma_f32_16x16x32_bf16 v[8:11], v[176:179], v[224:227], v[8:11]
	v_mfma_f32_16x16x32_bf16 v[12:15], v[168:171], v[232:235], v[12:15]
	v_mfma_f32_16x16x32_bf16 v[4:7], v[176:179], v[232:235], v[4:7]
